# S5 egemm/ygemm (P5,P7): unit index remapped so units sharing A/W tiles land on one XCD (on top of v4)
# speedup vs baseline: 1.0093x; 1.0093x over previous
; #define LAS __attribute__((address_space(3)))
; #define WSP(off) (PTR(29) + (off))
; __device__ __forceinline__ void s5_egemm(LAS unsigned char* lds, const bf16_t* Z, const bf16_t* W1, float* E, int unit, int tid) {
;     const int nh = unit & 3, mb3 = (unit >> 2) % 3, g = unit / 12;
;     const int wid = tid >> 6, lane = tid & 63, fr = lane & 15, fq = lane >> 4;
;     const int cbase = mb3 * 256 + wid * 32;
;     f32x4 acc[2][4];
; #pragma unroll
;     for (int m = 0; m < 2; ++m)
; #pragma unroll
;         for (int n = 0; n < 4; ++n) acc[m][n] = (f32x4){0.f, 0.f, 0.f, 0.f};
;     const bf16_t* Ab = Z + ((size_t)(g * S5NCB + (cbase >> 4)) * 32 + (fq >> 1)) * 256 + fr * 16 + (fq & 1) * 8;
;     const bf16_t* Bsrc = W1 + (size_t)g * 256 * 512 + (size_t)(nh * 64 + (tid >> 3)) * 512 + (tid & 7) * 8;
;     constexpr int ROWB = 144, BUFB = 64 * ROWB;
;     LAS unsigned char* bdst = lds + (tid >> 3) * ROWB + (tid & 7) * 16;
;     const LAS unsigned char* brd = lds + fr * ROWB + fq * 16;
;     u32x4 rb[5]; bf16x8 af[5][4];
; template <int K>
; __device__ __forceinline__ void run_phase(LAS unsigned char* lds, volatile LAS unsigned* ptab) {
;     ...
;     if constexpr (K == 5) { const bf16_t* Z = (const bf16_t*)WSP(WS_UG); const bf16_t* W1 = (const bf16_t*)WSP(WS_S5W1); float* E = (float*)WSP(WS_S5E);
;         for (int u = bx; u < 64 * 3 * 4; u += G) s5_egemm(lds, Z, W1, E, u, tid); }
.LBB0_637:
	s_or_b64 exec, exec, s[0:1]
	s_add_i32 s0, 0, 0x230ec
	v_mov_b32_e32 v4, v166
	s_waitcnt lgkmcnt(0)
	v_mov_b32_e32 v0, s0
	s_barrier
	ds_read_b32 v1, v0
	s_add_i32 s0, 0, 0x230e8
	v_mov_b32_e32 v2, s0
	ds_read_b32 v3, v2
	v_readlane_b32 s8, v252, 14
	s_waitcnt lgkmcnt(1)
	v_readfirstlane_b32 s1, v1
	ds_read_b32 v1, v0
	ds_read_b32 v5, v2
	ds_read_b32 v0, v0
	ds_read_b32 v2, v2
	v_readlane_b32 s9, v252, 15
	s_waitcnt lgkmcnt(4)
	v_readfirstlane_b32 s0, v3
	s_waitcnt lgkmcnt(3)
	v_readfirstlane_b32 s4, v1
	s_waitcnt lgkmcnt(2)
	v_readfirstlane_b32 s2, v5
	s_waitcnt lgkmcnt(1)
	v_readfirstlane_b32 s6, v0
	s_and_b64 vcc, exec, s[8:9]
	s_waitcnt lgkmcnt(0)
	v_readfirstlane_b32 s5, v2
	s_cbranch_vccnz .LBB0_640
	v_ashrrev_i32_e32 v0, 1, v4
	v_and_b32_e32 v8, 0xffffffe0, v0
	v_lshlrev_b32_e32 v0, 4, v4
	v_and_b32_e32 v9, 15, v4
	v_and_b32_e32 v0, 0x200, v0
	v_mov_b32_e32 v1, 0
	v_lshl_add_u64 v[2:3], s[0:1], 0, v[0:1]
	v_lshlrev_b32_e32 v0, 5, v9
	v_lshl_add_u64 v[2:3], v[2:3], 0, v[0:1]
	v_and_b32_e32 v0, 16, v4
	v_lshl_add_u64 v[2:3], v[2:3], 0, v[0:1]
	s_mov_b64 s[0:1], 0x14200000
	s_add_u32 s2, s2, 0x1b100000
	v_lshl_add_u64 v[2:3], v[2:3], 0, s[0:1]
	v_ashrrev_i32_e32 v10, 3, v4
	s_movk_i32 s0, 0x90
	s_addc_u32 s4, s4, 0
	v_bfe_u32 v5, v4, 4, 2
	v_and_b32_e32 v4, 7, v4
	v_mul_lo_u32 v6, v10, s0
	s_add_u32 s5, s5, 0x18100000
	v_lshlrev_b32_e32 v0, 3, v4
	v_lshlrev_b32_e32 v7, 4, v4
	v_lshlrev_b32_e32 v12, 4, v5
	v_add_u32_e32 v6, 0, v6
	v_mad_u32_u24 v13, v9, s0, 0
	v_lshlrev_b32_e32 v4, 2, v5
	s_addc_u32 s6, s6, 0
	s_lshl_b32 s8, s76, 6
	v_lshlrev_b32_e32 v0, 1, v0
	s_movk_i32 s9, 0x4000
	s_movk_i32 s10, 0x1000
	s_movk_i32 s11, 0x5000
	v_add_u32_e32 v11, v6, v7
	s_movk_i32 s12, 0x2000
	s_movk_i32 s13, 0x6000
	v_add_u32_e32 v12, v13, v12
	s_movk_i32 s14, 0x3000
	s_movk_i32 s15, 0x7000
	v_lshlrev_b32_e32 v4, 2, v4
	v_mov_b32_e32 v5, v1
	s_and_b32 s16, s3, 7
	s_lshl_b32 s16, s16, 5
	s_lshr_b32 s7, s3, 3
	s_or_b32 s16, s16, s7
	s_cmp_eq_u32 s76, 0x100
	s_cselect_b32 s16, s16, s3
	s_lshl_b32 s7, s16, 6

; #define LAS __attribute__((address_space(3)))
; #define WSP(off) (PTR(29) + (off))
; __device__ __forceinline__ void s5_ygemm(LAS unsigned char* lds, const bf16_t* Z, const bf16_t* W3, const float* E, bf16_t* YG, int unit, int tid) {
;     const int nq = unit & 3, mb3 = (unit >> 2) % 3, g = unit / 12;
;     const int wid = tid >> 6, lane = tid & 63, fr = lane & 15, fq = lane >> 4;
;     const int cbase = mb3 * 256 + wid * 32;
;     f32x4 acc[2][8];
; #pragma unroll
;     for (int m = 0; m < 2; ++m)
; #pragma unroll
;         for (int n = 0; n < 8; ++n) acc[m][n] = (f32x4){0.f, 0.f, 0.f, 0.f};
;     const bf16_t* Ab = Z + ((size_t)(g * S5NCB + (cbase >> 4)) * 32 + (fq >> 1)) * 256 + fr * 16 + (fq & 1) * 8;
;     const bf16_t* Xb = (const bf16_t*)(E + (size_t)(cbase + fr) * 16384 + g * 256) + fq * 8;
;     const bf16_t* Bsrc = W3 + (size_t)g * 512 * 768 + (size_t)(nq * 128 + (tid >> 3)) * 768 + (tid & 7) * 8;
;     constexpr int ROWB = 144, BUFB = 128 * ROWB;
;     LAS unsigned char* bdst = lds + (tid >> 3) * ROWB + (tid & 7) * 16;
;     const LAS unsigned char* brd = lds + fr * ROWB + fq * 16;
; template <int K>
; __device__ __forceinline__ void run_phase(LAS unsigned char* lds, volatile LAS unsigned* ptab) {
;     ...
;     if constexpr (K == 7) { const bf16_t* Z = (const bf16_t*)WSP(WS_UG); const bf16_t* W3 = (const bf16_t*)WSP(WS_S5W3); const float* E = (const float*)WSP(WS_S5E); bf16_t* YG = (bf16_t*)WSP(WS_XN);
;         for (int u = bx; u < 64 * 3 * 4; u += G) s5_ygemm(lds, Z, W3, E, YG, u, tid); }
.LBB0_753:
	s_or_b64 exec, exec, s[0:1]
	s_add_i32 s0, 0, 0x230ec
	s_waitcnt lgkmcnt(0)
	v_mov_b32_e32 v0, v166
	v_mov_b32_e32 v1, s0
	s_barrier
	ds_read_b32 v2, v1
	s_add_i32 s0, 0, 0x230e8
	v_mov_b32_e32 v3, s0
	ds_read_b32 v4, v3
	ds_read_b32 v5, v1
	v_readlane_b32 s12, v252, 14
	s_waitcnt lgkmcnt(2)
	v_readfirstlane_b32 s7, v2
	ds_read_b32 v2, v3
	s_waitcnt lgkmcnt(2)
	v_readfirstlane_b32 s6, v4
	s_waitcnt lgkmcnt(1)
	v_readfirstlane_b32 s0, v5
	ds_read_b32 v4, v1
	ds_read_b32 v5, v3
	ds_read_b32 v1, v1
	v_readlane_b32 s13, v252, 15
	s_waitcnt lgkmcnt(3)
	v_readfirstlane_b32 s1, v2
	ds_read_b32 v2, v3
	s_waitcnt lgkmcnt(3)
	v_readfirstlane_b32 s9, v4
	s_waitcnt lgkmcnt(2)
	v_readfirstlane_b32 s10, v5
	s_waitcnt lgkmcnt(1)
	v_readfirstlane_b32 s5, v1
	s_and_b64 vcc, exec, s[12:13]
	s_waitcnt lgkmcnt(0)
	v_readfirstlane_b32 s4, v2
	s_cbranch_vccnz .LBB0_756
	v_ashrrev_i32_e32 v2, 1, v0
	v_and_b32_e32 v142, 0xffffffe0, v2
	v_lshlrev_b32_e32 v2, 4, v0
	v_and_b32_e32 v143, 15, v0
	v_and_b32_e32 v124, 0x200, v2
	v_mov_b32_e32 v125, 0
	v_lshl_add_u64 v[2:3], s[6:7], 0, v[124:125]
	v_lshlrev_b32_e32 v124, 5, v143
	v_lshl_add_u64 v[2:3], v[2:3], 0, v[124:125]
	v_and_b32_e32 v124, 16, v0
	v_lshl_add_u64 v[2:3], v[2:3], 0, v[124:125]
	s_mov_b64 s[6:7], 0x14200000
	s_add_u32 s2, s1, 0x1c100000
	v_bfe_u32 v1, v0, 4, 2
	v_lshl_add_u64 v[126:127], v[2:3], 0, s[6:7]
	v_ashrrev_i32_e32 v144, 3, v0
	v_and_b32_e32 v2, 7, v0
	s_movk_i32 s6, 0x90
	s_addc_u32 s8, s0, 0
	v_lshlrev_b32_e32 v124, 3, v1
	v_lshlrev_b32_e32 v0, 3, v2
	v_mul_lo_u32 v3, v144, s6
	v_lshlrev_b32_e32 v4, 4, v2
	v_mul_u32_u24_e32 v2, 0x90, v143
	v_lshlrev_b32_e32 v1, 4, v1
	s_add_u32 s0, s10, 0x18100000
	v_add_u32_e32 v5, 0, v3
	v_add3_u32 v145, 0, v2, v1
	v_lshl_add_u64 v[2:3], s[4:5], 0, v[124:125]
	s_mov_b64 s[4:5], 0x2200000
	s_addc_u32 s1, s9, 0
	v_lshl_add_u64 v[128:129], v[2:3], 0, s[4:5]
	s_movk_i32 s6, 0x600
	v_lshlrev_b32_e32 v130, 1, v0
	v_mov_b32_e32 v131, v125
	s_mov_b32 s7, 0x18000
	s_movk_i32 s9, 0x4000
	s_movk_i32 s10, 0x1000
	s_movk_i32 s11, 0x5000
	v_lshlrev_b32_e32 v124, 1, v124
	v_add_u32_e32 v146, v5, v4
	s_movk_i32 s12, 0x2000
	s_movk_i32 s13, 0x6000
	s_movk_i32 s14, 0x3000
	s_movk_i32 s15, 0x7000
	s_mov_b32 s16, 0x100000
	s_mov_b32 s17, 0x7060302
	s_and_b32 s18, s3, 7
	s_lshl_b32 s18, s18, 5
	s_lshr_b32 s19, s3, 3
	s_or_b32 s18, s18, s19
	s_cmp_eq_u32 s76, 0x100
	s_cselect_b32 s18, s18, s3
